# ssd state reads batched + out-proj layer-0 epilogue residual loads pipelined 3 steps ahead (counted vmcnt)
# speedup vs baseline: 1.0174x; 1.0039x over previous
; __device__ __forceinline__ unsigned cvt_pk_bf16(float lo, float hi) { unsigned r; asm volatile("v_cvt_pk_bf16_f32 %0, %1, %2" : "=v"(r) : "v"(lo), "v"(hi)); return r; }
; __device__ __forceinline__ float bflo(unsigned u) { return __uint_as_float(u << 16); }
; __device__ __forceinline__ float bfhi(unsigned u) { return __uint_as_float(u & 0xffff0000u); }
; #define LAS __attribute__((address_space(3)))
; __device__ __forceinline__ s16x4 ldtr(LAS unsigned char* p) { return __builtin_bit_cast(s16x4, __builtin_amdgcn_ds_read_tr16_b64_v4i16((LAS v4i16_t*)p)); }
; __device__ __forceinline__ bf16x8 cat8(s16x4 lo, s16x4 hi) { return (bf16x8){lo[0], lo[1], lo[2], lo[3], hi[0], hi[1], hi[2], hi[3]}; }
; template <int VAR, bool SIDE> ...
;     ...
;             for (int pt = 0; pt < 4; ++pt) { const int p0 = 16 * pt + 4 * q4;
;                 const u32x2 xv = *(const LAS u32x2*)(Xs + l * XS + p0 * 2);
;                 const f32x4 xf = {bflo(xv.x), bfhi(xv.x), bflo(xv.y), bfhi(xv.y)}, zf = {bflo(zv[pt].x), bfhi(zv[pt].x), bflo(zv[pt].y), bfhi(zv[pt].y)};
;                 const f32x4 yv = (Y[pt] + Dk * xf) * zf;
;                 u32x2 pk; pk.x = cvt_pk_bf16(yv[0], yv[1]); pk.y = cvt_pk_bf16(yv[2], yv[3]); if (!(VAR & 1)) *(u32x2*)(zp + 16 * pt) = pk; else asm volatile("" :: "v"(pk.x), "v"(pk.y)); }
;             __builtin_amdgcn_sched_barrier(0);
;             const float et = __builtin_amdgcn_exp2f(acum[127]);
; #pragma unroll
;             for (int pt = 0; pt < 4; ++pt) hacc[pt] *= et;
;             LAS unsigned char* btbase = Bm + (4 * q4 + (l15 >> 2)) * BS + (16 * wave + 4 * (l15 & 3)) * 2;
;             LAS unsigned char* xwbase = Xw + (4 * q4 + (l15 >> 2)) * XS + (l15 & 3) * 8;
; #pragma unroll
;             for (int kk = 0; kk < 4; ++kk) {
;                 const s16x4 blo = ldtr(btbase + (32 * kk) * BS);
;                 const s16x4 bhi = ldtr(btbase + (32 * kk + 16) * BS);
;                 const bf16x8 Bf = cat8(blo, bhi);
; #pragma unroll
;                 for (int pt = 0; pt < 4; ++pt) {
;                     const s16x4 xlo = ldtr(xwbase + (32 * kk) * XS + pt * 32);
;                     const s16x4 xhi = ldtr(xwbase + (32 * kk + 16) * XS + pt * 32);
;                     hacc[pt] = mfma16(Bf, cat8(xlo, xhi), hacc[pt]); }
;             }
.Lssd_pfdone:
	v_lshlrev_b32_e32 v90, 16, v152
	v_and_b32_e32 v91, 0xffff0000, v152
	v_mov_b32_e32 v105, v104
	v_lshlrev_b32_e32 v94, 16, v153
	s_waitcnt lgkmcnt(0)
	v_lshlrev_b32_e32 v92, 16, v88
	v_and_b32_e32 v93, 0xffff0000, v88
	v_lshlrev_b32_e32 v88, 16, v89
	v_and_b32_e32 v89, 0xffff0000, v89
	v_pk_fma_f32 v[84:85], v[110:111], v[92:93], v[84:85]
	v_and_b32_e32 v95, 0xffff0000, v153
	v_pk_fma_f32 v[86:87], v[104:105], v[88:89], v[86:87]
	v_pk_mul_f32 v[84:85], v[84:85], v[90:91]
	v_pk_mul_f32 v[86:87], v[86:87], v[94:95]
	v_cvt_pk_bf16_f32 v84, v84, v85
	v_lshlrev_b32_e32 v88, 16, v150
	v_cvt_pk_bf16_f32 v85, v86, v87
	global_store_dwordx2 v[144:145], v[84:85], off
	ds_read_b64 v[84:85], v241 offset:32
	v_and_b32_e32 v89, 0xffff0000, v150
	v_lshlrev_b32_e32 v90, 16, v151
	v_and_b32_e32 v91, 0xffff0000, v151
	s_waitcnt lgkmcnt(0)
	v_lshlrev_b32_e32 v86, 16, v84
	v_and_b32_e32 v87, 0xffff0000, v84
	v_lshlrev_b32_e32 v84, 16, v85
	v_and_b32_e32 v85, 0xffff0000, v85
	v_pk_fma_f32 v[80:81], v[110:111], v[86:87], v[80:81]
	v_pk_fma_f32 v[82:83], v[104:105], v[84:85], v[82:83]
	v_pk_mul_f32 v[80:81], v[80:81], v[88:89]
	v_pk_mul_f32 v[82:83], v[82:83], v[90:91]
	v_cvt_pk_bf16_f32 v80, v80, v81
	v_lshlrev_b32_e32 v84, 16, v148
	v_cvt_pk_bf16_f32 v81, v82, v83
	global_store_dwordx2 v[144:145], v[80:81], off offset:32
	ds_read_b64 v[80:81], v241 offset:64
	v_and_b32_e32 v85, 0xffff0000, v148
	v_lshlrev_b32_e32 v86, 16, v149
	v_and_b32_e32 v87, 0xffff0000, v149
	s_waitcnt lgkmcnt(0)
	v_lshlrev_b32_e32 v82, 16, v80
	v_and_b32_e32 v83, 0xffff0000, v80
	v_lshlrev_b32_e32 v80, 16, v81
	v_and_b32_e32 v81, 0xffff0000, v81
	v_pk_fma_f32 v[76:77], v[110:111], v[82:83], v[76:77]
	v_pk_fma_f32 v[78:79], v[104:105], v[80:81], v[78:79]
	v_pk_mul_f32 v[76:77], v[76:77], v[84:85]
	v_pk_mul_f32 v[78:79], v[78:79], v[86:87]
	v_cvt_pk_bf16_f32 v76, v76, v77
	v_lshlrev_b32_e32 v80, 16, v146
	v_cvt_pk_bf16_f32 v77, v78, v79
	global_store_dwordx2 v[144:145], v[76:77], off offset:64
	ds_read_b64 v[76:77], v241 offset:96
	v_and_b32_e32 v81, 0xffff0000, v146
	v_lshlrev_b32_e32 v82, 16, v147
	v_and_b32_e32 v83, 0xffff0000, v147
	s_waitcnt lgkmcnt(0)
	v_lshlrev_b32_e32 v78, 16, v76
	v_and_b32_e32 v79, 0xffff0000, v76
	v_lshlrev_b32_e32 v76, 16, v77
	v_and_b32_e32 v77, 0xffff0000, v77
	v_pk_fma_f32 v[72:73], v[110:111], v[78:79], v[72:73]
	v_pk_fma_f32 v[74:75], v[104:105], v[76:77], v[74:75]
	v_pk_mul_f32 v[72:73], v[72:73], v[80:81]
	v_pk_mul_f32 v[74:75], v[74:75], v[82:83]
	v_cvt_pk_bf16_f32 v72, v72, v73
	s_nop 0
	v_cvt_pk_bf16_f32 v73, v74, v75
	global_store_dwordx2 v[144:145], v[72:73], off offset:96
	v_mov_b32_e32 v72, s33
	ds_read_b32 v72, v72 offset:508
	s_or_b64 s[18:19], s[78:79], s[18:19]
	s_and_b64 vcc, exec, s[18:19]
	s_waitcnt lgkmcnt(0)
	v_exp_f32_e32 v72, v72
	s_nop 0
	v_pk_mul_f32 v[58:59], v[58:59], v[72:73] op_sel_hi:[1,0]
	v_pk_mul_f32 v[56:57], v[56:57], v[72:73] op_sel_hi:[1,0]
	v_pk_mul_f32 v[62:63], v[62:63], v[72:73] op_sel_hi:[1,0]
	v_pk_mul_f32 v[60:61], v[60:61], v[72:73] op_sel_hi:[1,0]
	v_pk_mul_f32 v[66:67], v[66:67], v[72:73] op_sel_hi:[1,0]
	v_pk_mul_f32 v[64:65], v[64:65], v[72:73] op_sel_hi:[1,0]
	v_pk_mul_f32 v[70:71], v[70:71], v[72:73] op_sel_hi:[1,0]
	v_pk_mul_f32 v[68:69], v[68:69], v[72:73] op_sel_hi:[1,0]
	ds_read_b64_tr_b16 v[72:73], v229 offset:36864
	ds_read_b64_tr_b16 v[74:75], v229 offset:41216
	ds_read_b64_tr_b16 v[76:77], v2 offset:18432
	ds_read_b64_tr_b16 v[78:79], v2 offset:20736
	ds_read_b64_tr_b16 v[80:81], v2 offset:18464
	ds_read_b64_tr_b16 v[82:83], v2 offset:20768
	ds_read_b64_tr_b16 v[84:85], v2 offset:18496
	ds_read_b64_tr_b16 v[86:87], v2 offset:20800
	ds_read_b64_tr_b16 v[88:89], v2 offset:18528
	ds_read_b64_tr_b16 v[90:91], v2 offset:20832
	s_waitcnt lgkmcnt(6)
	v_mfma_f32_16x16x32_bf16 v[56:59], v[72:75], v[76:79], v[56:59]
	s_waitcnt lgkmcnt(4)
	v_mfma_f32_16x16x32_bf16 v[60:63], v[72:75], v[80:83], v[60:63]
	s_waitcnt lgkmcnt(2)
	v_mfma_f32_16x16x32_bf16 v[64:67], v[72:75], v[84:87], v[64:67]
	s_waitcnt lgkmcnt(0)
	v_mfma_f32_16x16x32_bf16 v[68:71], v[72:75], v[88:91], v[68:71]
	ds_read_b64_tr_b16 v[72:73], v229 offset:45568
	ds_read_b64_tr_b16 v[74:75], v229 offset:49920
	ds_read_b64_tr_b16 v[76:77], v2 offset:23040
	ds_read_b64_tr_b16 v[78:79], v2 offset:25344
	ds_read_b64_tr_b16 v[80:81], v2 offset:23072
	ds_read_b64_tr_b16 v[82:83], v2 offset:25376
	ds_read_b64_tr_b16 v[84:85], v2 offset:23104
	ds_read_b64_tr_b16 v[86:87], v2 offset:25408
	ds_read_b64_tr_b16 v[88:89], v2 offset:23136
	ds_read_b64_tr_b16 v[90:91], v2 offset:25440
	s_waitcnt lgkmcnt(6)
	v_mfma_f32_16x16x32_bf16 v[56:59], v[72:75], v[76:79], v[56:59]
	s_waitcnt lgkmcnt(4)
	v_mfma_f32_16x16x32_bf16 v[60:63], v[72:75], v[80:83], v[60:63]
	s_waitcnt lgkmcnt(2)
	v_mfma_f32_16x16x32_bf16 v[64:67], v[72:75], v[84:87], v[64:67]
	s_waitcnt lgkmcnt(0)
	v_mfma_f32_16x16x32_bf16 v[68:71], v[72:75], v[88:91], v[68:71]
	ds_read_b64_tr_b16 v[72:73], v229 offset:54272
	ds_read_b64_tr_b16 v[74:75], v229 offset:58624
	ds_read_b64_tr_b16 v[76:77], v2 offset:27648
	ds_read_b64_tr_b16 v[78:79], v2 offset:29952
	ds_read_b64_tr_b16 v[80:81], v2 offset:27680
	ds_read_b64_tr_b16 v[82:83], v2 offset:29984
	ds_read_b64_tr_b16 v[84:85], v2 offset:27712
	ds_read_b64_tr_b16 v[86:87], v2 offset:30016
	ds_read_b64_tr_b16 v[88:89], v2 offset:27744
	ds_read_b64_tr_b16 v[90:91], v2 offset:30048
	s_waitcnt lgkmcnt(6)
	v_mfma_f32_16x16x32_bf16 v[56:59], v[72:75], v[76:79], v[56:59]
	s_waitcnt lgkmcnt(4)
	v_mfma_f32_16x16x32_bf16 v[60:63], v[72:75], v[80:83], v[60:63]
	s_waitcnt lgkmcnt(2)
	v_mfma_f32_16x16x32_bf16 v[64:67], v[72:75], v[84:87], v[64:67]
	s_waitcnt lgkmcnt(0)
	v_mfma_f32_16x16x32_bf16 v[68:71], v[72:75], v[88:91], v[68:71]
	ds_read_b64_tr_b16 v[72:73], v229 offset:62976
	ds_read_b64_tr_b16 v[74:75], v230 offset:30464
	ds_read_b64_tr_b16 v[76:77], v2 offset:32256
	ds_read_b64_tr_b16 v[78:79], v2 offset:34560
	ds_read_b64_tr_b16 v[80:81], v2 offset:32288
	ds_read_b64_tr_b16 v[82:83], v2 offset:34592
	ds_read_b64_tr_b16 v[84:85], v2 offset:32320
	ds_read_b64_tr_b16 v[86:87], v2 offset:34624
	ds_read_b64_tr_b16 v[88:89], v2 offset:32352
	ds_read_b64_tr_b16 v[90:91], v2 offset:34656
	s_waitcnt lgkmcnt(6)
	v_mfma_f32_16x16x32_bf16 v[56:59], v[72:75], v[76:79], v[56:59]
	s_waitcnt lgkmcnt(4)
	v_mfma_f32_16x16x32_bf16 v[60:63], v[72:75], v[80:83], v[60:63]
	s_waitcnt lgkmcnt(2)
	v_mfma_f32_16x16x32_bf16 v[64:67], v[72:75], v[84:87], v[64:67]
	s_waitcnt lgkmcnt(0)
	v_mfma_f32_16x16x32_bf16 v[68:71], v[72:75], v[88:91], v[68:71]
	s_cbranch_vccnz .LBB0_410
	v_add_f32_e32 v2, v200, v211
	v_add_f32_e32 v72, v200, v212
	v_mul_f32_e32 v73, 0x3fb8aa3b, v2
	v_mul_f32_e32 v74, 0x3fb8aa3b, v72
	v_exp_f32_e32 v73, v73
	v_exp_f32_e32 v74, v74
	s_nop 0
	v_add_f32_e32 v75, 1.0, v73
	v_add_f32_e32 v76, 1.0, v74
	v_add_f32_e32 v77, -1.0, v75
	v_add_f32_e32 v78, -1.0, v76
	v_log_f32_e32 v75, v75
	v_log_f32_e32 v76, v76
	v_rcp_f32_e32 v79, v77
	v_rcp_f32_e32 v80, v78
	s_nop 0
	v_mul_f32_e32 v75, 0x3f317218, v75
	v_mul_f32_e32 v76, 0x3f317218, v76
	v_mul_f32_e32 v79, v73, v79
	v_mul_f32_e32 v80, v74, v80
	v_mul_f32_e32 v75, v75, v79
	v_mul_f32_e32 v76, v76, v80
	v_cmp_eq_f32_e32 vcc, 0, v77
	s_nop 1
	v_cndmask_b32_e32 v75, v75, v73, vcc
	v_cmp_eq_f32_e32 vcc, 0, v78
	s_nop 1
	v_cndmask_b32_e32 v76, v76, v74, vcc
	v_cmp_lt_f32_e32 vcc, s28, v2
	s_nop 1
	v_cndmask_b32_e32 v2, v75, v2, vcc
	v_cmp_lt_f32_e32 vcc, s28, v72
	s_nop 1
	v_cndmask_b32_e32 v72, v76, v72, vcc
	s_branch .LBB0_409

; __device__ __forceinline__ unsigned cvt_pk_bf16(float lo, float hi) { unsigned r; asm volatile("v_cvt_pk_bf16_f32 %0, %1, %2" : "=v"(r) : "v"(lo), "v"(hi)); return r; }
;     __device__ __forceinline__ void operator()(const f32x4 (&acc)[2][2][4][2], const Unit& u, int wr, int wc, int fr, int fq) const {
;         const int row0 = u.pm * BM + wr * 64 + fr; const int col0 = u.pn * BM + wc * 32 + 8 * fq;
;         const float* gp = gate + (size_t)(u.pm >> 4) * gstride + col0;
;         f32x4 g0[2], g1[2];
; #pragma unroll
;         for (int bj = 0; bj < 2; ++bj) { g0[bj] = *(const f32x4*)(gp + bj * HALF); g1[bj] = *(const f32x4*)(gp + bj * HALF + 4); }
;         if (xin_f) {
; #pragma unroll
;             for (int ai = 0; ai < 2; ++ai)
; #pragma unroll
;                 for (int m = 0; m < 4; ++m) { const size_t off = (size_t)(row0 + ai * HALF + m * 16) * 2048 + col0;
; #pragma unroll
;                     for (int bj = 0; bj < 2; ++bj) { const f32x4 x0 = *(const f32x4*)(xin_f + off + bj * HALF), x1 = *(const f32x4*)(xin_f + off + bj * HALF + 4);
;                         const f32x4 v0 = x0 + g0[bj] * acc[ai][bj][m][0], v1 = x1 + g1[bj] * acc[ai][bj][m][1];
;                         u32x4 w; w.x = cvt_pk_bf16(v0[0], v0[1]); w.y = cvt_pk_bf16(v0[2], v0[3]); w.z = cvt_pk_bf16(v1[0], v1[1]); w.w = cvt_pk_bf16(v1[2], v1[3]);
;                         *(u32x4*)(out + off + bj * HALF) = w; } }
.LBB0_664:
	s_ashr_i32 s5, s33, 4
	s_mul_hi_i32 s7, s5, 0xc000
	s_mul_i32 s5, s5, 0xc000
	v_lshl_or_b32 v154, s56, 8, v212
	s_add_u32 s18, s52, s5
	s_addc_u32 s19, s53, s7
	v_ashrrev_i32_e32 v155, 31, v154
	v_lshl_add_u64 v[108:109], v[154:155], 2, s[18:19]
	flat_load_dwordx4 v[120:123], v[108:109]
	flat_load_dwordx4 v[116:119], v[108:109] offset:16
	flat_load_dwordx4 v[112:115], v[108:109] offset:512
	s_nop 0
	flat_load_dwordx4 v[108:111], v[108:109] offset:528
	v_lshl_add_u32 v160, s33, 8, v173
	v_or_b32_e32 v158, 16, v160
	v_or_b32_e32 v156, 32, v160
	v_or_b32_e32 v152, 48, v160
	v_readlane_b32 s66, v252, 18
	s_andn2_b64 vcc, exec, s[40:41]
	v_ashrrev_i32_e32 v161, 31, v160
	v_ashrrev_i32_e32 v159, 31, v158
	v_ashrrev_i32_e32 v157, 31, v156
	v_ashrrev_i32_e32 v153, 31, v152
	v_readlane_b32 s67, v252, 19
	s_cbranch_vccnz .LBB0_670
	v_lshlrev_b64 v[148:149], 11, v[160:161]
	v_lshl_add_u64 v[148:149], v[148:149], 0, v[154:155]
	v_lshl_add_u64 v[150:151], v[148:149], 2, s[24:25]
	v_mov_b32_e32 v228, v148
	v_mov_b32_e32 v229, v149
	v_lshl_add_u64 v[228:229], v[228:229], 2, s[24:25]
	global_load_dwordx4 v[232:235], v[228:229], off offset:16
	s_nop 0
	global_load_dwordx4 v[228:231], v[228:229], off
	v_mov_b32_e32 v236, v148
	v_mov_b32_e32 v237, v149
	v_lshl_add_u64 v[236:237], v[236:237], 2, s[24:25]
	global_load_dwordx4 v[240:243], v[236:237], off offset:528
	s_nop 0
	global_load_dwordx4 v[236:239], v[236:237], off offset:512
	v_add_co_u32_e32 v244, vcc, 0x8000, v148
	s_nop 1
	v_addc_co_u32_e32 v245, vcc, 0, v149, vcc
	v_lshl_add_u64 v[244:245], v[244:245], 2, s[24:25]
	global_load_dwordx4 v[248:251], v[244:245], off offset:16
	s_nop 0
	global_load_dwordx4 v[244:247], v[244:245], off
	s_mov_b64 s[18:19], 0x40000
	s_waitcnt vmcnt(4) lgkmcnt(0)
	v_pk_fma_f32 v[166:167], v[146:147], v[122:123], v[230:231]
	v_pk_fma_f32 v[190:191], v[144:145], v[120:121], v[228:229]
	v_pk_fma_f32 v[192:193], v[142:143], v[118:119], v[234:235]
	v_pk_fma_f32 v[164:165], v[140:141], v[116:117], v[232:233]
	v_add_co_u32_e32 v228, vcc, 0x8000, v148
	s_nop 1
	v_addc_co_u32_e32 v229, vcc, 0, v149, vcc
	v_lshl_add_u64 v[228:229], v[228:229], 2, s[24:25]
	global_load_dwordx4 v[232:235], v[228:229], off offset:528
	s_nop 0
	global_load_dwordx4 v[228:231], v[228:229], off offset:512
	v_cvt_pk_bf16_f32 v162, v190, v191
	v_cvt_pk_bf16_f32 v163, v166, v167
	v_lshl_add_u64 v[166:167], v[148:149], 1, s[20:21]
	v_cvt_pk_bf16_f32 v164, v164, v165
	v_cvt_pk_bf16_f32 v165, v192, v193
	flat_store_dwordx4 v[166:167], v[162:165]
	s_waitcnt vmcnt(5)
	v_pk_fma_f32 v[150:151], v[130:131], v[114:115], v[238:239]
	v_pk_fma_f32 v[190:191], v[128:129], v[112:113], v[236:237]
	v_pk_fma_f32 v[192:193], v[126:127], v[110:111], v[242:243]
	v_pk_fma_f32 v[164:165], v[124:125], v[108:109], v[240:241]
	v_add_co_u32_e32 v236, vcc, 0x10000, v148
	s_nop 1
	v_addc_co_u32_e32 v237, vcc, 0, v149, vcc
	v_lshl_add_u64 v[236:237], v[236:237], 2, s[24:25]
	global_load_dwordx4 v[240:243], v[236:237], off offset:16
	s_nop 0
	global_load_dwordx4 v[236:239], v[236:237], off
	v_cvt_pk_bf16_f32 v162, v190, v191
	v_cvt_pk_bf16_f32 v163, v150, v151
	v_lshlrev_b64 v[150:151], 11, v[158:159]
	v_lshl_add_u64 v[150:151], v[150:151], 0, v[154:155]
	v_cvt_pk_bf16_f32 v164, v164, v165
	v_cvt_pk_bf16_f32 v165, v192, v193
	flat_store_dwordx4 v[166:167], v[162:165] offset:256
	v_lshl_add_u64 v[166:167], v[150:151], 2, s[24:25]
	v_lshl_add_u64 v[150:151], v[150:151], 1, s[20:21]
	s_waitcnt vmcnt(6)
	v_pk_fma_f32 v[194:195], v[134:135], v[118:119], v[250:251]
	v_pk_fma_f32 v[164:165], v[132:133], v[116:117], v[248:249]
	v_pk_fma_f32 v[192:193], v[138:139], v[122:123], v[246:247]
	v_pk_fma_f32 v[190:191], v[136:137], v[120:121], v[244:245]
	v_add_co_u32_e32 v244, vcc, 0x10000, v148
	s_nop 1
	v_addc_co_u32_e32 v245, vcc, 0, v149, vcc
	v_lshl_add_u64 v[244:245], v[244:245], 2, s[24:25]
	global_load_dwordx4 v[248:251], v[244:245], off offset:528
	s_nop 0
	global_load_dwordx4 v[244:247], v[244:245], off offset:512
	s_nop 0
	v_cvt_pk_bf16_f32 v162, v190, v191
	v_cvt_pk_bf16_f32 v163, v192, v193
	v_cvt_pk_bf16_f32 v164, v164, v165
	v_cvt_pk_bf16_f32 v165, v194, v195
	flat_store_dwordx4 v[150:151], v[162:165]
	s_waitcnt vmcnt(7)
	v_pk_fma_f32 v[166:167], v[106:107], v[114:115], v[230:231]
	v_pk_fma_f32 v[192:193], v[102:103], v[110:111], v[234:235]
	v_pk_fma_f32 v[164:165], v[100:101], v[108:109], v[232:233]
	v_pk_fma_f32 v[190:191], v[104:105], v[112:113], v[228:229]
	v_add_co_u32_e32 v228, vcc, 0x18000, v148
	s_nop 1
	v_addc_co_u32_e32 v229, vcc, 0, v149, vcc
	v_lshl_add_u64 v[228:229], v[228:229], 2, s[24:25]
	global_load_dwordx4 v[232:235], v[228:229], off offset:16
	s_nop 0
	global_load_dwordx4 v[228:231], v[228:229], off
	s_nop 0
	v_cvt_pk_bf16_f32 v162, v190, v191
	v_cvt_pk_bf16_f32 v163, v166, v167
	v_cvt_pk_bf16_f32 v164, v164, v165
	v_cvt_pk_bf16_f32 v165, v192, v193
	flat_store_dwordx4 v[150:151], v[162:165] offset:256
	v_lshlrev_b64 v[150:151], 11, v[156:157]
	v_lshl_add_u64 v[150:151], v[150:151], 0, v[154:155]
	v_lshl_add_u64 v[166:167], v[150:151], 2, s[24:25]
	v_lshl_add_u64 v[150:151], v[150:151], 1, s[20:21]
	s_waitcnt vmcnt(7)
	v_pk_fma_f32 v[194:195], v[94:95], v[118:119], v[242:243]
	v_pk_fma_f32 v[164:165], v[92:93], v[116:117], v[240:241]
	v_pk_fma_f32 v[192:193], v[98:99], v[122:123], v[238:239]
	v_pk_fma_f32 v[190:191], v[96:97], v[120:121], v[236:237]
	v_add_co_u32_e32 v236, vcc, 0x18000, v148
	s_nop 1
	v_addc_co_u32_e32 v237, vcc, 0, v149, vcc
	v_lshl_add_u64 v[236:237], v[236:237], 2, s[24:25]
	global_load_dwordx4 v[240:243], v[236:237], off offset:528
	s_nop 0
	global_load_dwordx4 v[236:239], v[236:237], off offset:512
	s_nop 0
	v_cvt_pk_bf16_f32 v162, v190, v191
	v_cvt_pk_bf16_f32 v163, v192, v193
	v_cvt_pk_bf16_f32 v164, v164, v165
	v_cvt_pk_bf16_f32 v165, v194, v195
	flat_store_dwordx4 v[150:151], v[162:165]
	s_waitcnt vmcnt(7)
; __device__ __forceinline__ unsigned cvt_pk_bf16(float lo, float hi) { unsigned r; asm volatile("v_cvt_pk_bf16_f32 %0, %1, %2" : "=v"(r) : "v"(lo), "v"(hi)); return r; }
;     __device__ __forceinline__ void operator()(const f32x4 (&acc)[2][2][4][2], const Unit& u, int wr, int wc, int fr, int fq) const {
;     ...
;                 for (int m = 0; m < 4; ++m) { const size_t off = (size_t)(row0 + ai * HALF + m * 16) * 2048 + col0;
; #pragma unroll
;                     for (int bj = 0; bj < 2; ++bj) { const f32x4 x0 = *(const f32x4*)(xin_f + off + bj * HALF), x1 = *(const f32x4*)(xin_f + off + bj * HALF + 4);
;                         const f32x4 v0 = x0 + g0[bj] * acc[ai][bj][m][0], v1 = x1 + g1[bj] * acc[ai][bj][m][1];
;                         u32x4 w; w.x = cvt_pk_bf16(v0[0], v0[1]); w.y = cvt_pk_bf16(v0[2], v0[3]); w.z = cvt_pk_bf16(v1[0], v1[1]); w.w = cvt_pk_bf16(v1[2], v1[3]);
;                         *(u32x4*)(out + off + bj * HALF) = w; } }
	v_pk_fma_f32 v[166:167], v[90:91], v[114:115], v[246:247]
	v_pk_fma_f32 v[192:193], v[86:87], v[110:111], v[250:251]
	v_pk_fma_f32 v[164:165], v[84:85], v[108:109], v[248:249]
	v_pk_fma_f32 v[190:191], v[88:89], v[112:113], v[244:245]
	v_add_co_u32_e32 v244, vcc, 0x40000, v148
	s_nop 1
	v_addc_co_u32_e32 v245, vcc, 0, v149, vcc
	v_lshl_add_u64 v[244:245], v[244:245], 2, s[24:25]
	global_load_dwordx4 v[248:251], v[244:245], off offset:16
	s_nop 0
	global_load_dwordx4 v[244:247], v[244:245], off
	s_nop 0
	v_cvt_pk_bf16_f32 v162, v190, v191
	v_cvt_pk_bf16_f32 v163, v166, v167
	v_cvt_pk_bf16_f32 v164, v164, v165
	v_cvt_pk_bf16_f32 v165, v192, v193
	flat_store_dwordx4 v[150:151], v[162:165] offset:256
	v_lshlrev_b64 v[150:151], 11, v[152:153]
	v_lshl_add_u64 v[150:151], v[150:151], 0, v[154:155]
	v_lshl_add_u64 v[166:167], v[150:151], 2, s[24:25]
	v_lshl_add_u64 v[150:151], v[150:151], 1, s[20:21]
	s_waitcnt vmcnt(7)
	v_pk_fma_f32 v[194:195], v[78:79], v[118:119], v[234:235]
	v_pk_fma_f32 v[164:165], v[76:77], v[116:117], v[232:233]
	v_pk_fma_f32 v[192:193], v[82:83], v[122:123], v[230:231]
	v_pk_fma_f32 v[190:191], v[80:81], v[120:121], v[228:229]
	v_add_co_u32_e32 v228, vcc, 0x40000, v148
	s_nop 1
	v_addc_co_u32_e32 v229, vcc, 0, v149, vcc
	v_lshl_add_u64 v[228:229], v[228:229], 2, s[24:25]
	global_load_dwordx4 v[232:235], v[228:229], off offset:528
	s_nop 0
	global_load_dwordx4 v[228:231], v[228:229], off offset:512
	s_nop 0
	v_cvt_pk_bf16_f32 v162, v190, v191
	v_cvt_pk_bf16_f32 v163, v192, v193
	v_cvt_pk_bf16_f32 v164, v164, v165
	v_cvt_pk_bf16_f32 v165, v194, v195
	flat_store_dwordx4 v[150:151], v[162:165]
	s_waitcnt vmcnt(7)
	v_pk_fma_f32 v[166:167], v[74:75], v[114:115], v[238:239]
	v_pk_fma_f32 v[192:193], v[70:71], v[110:111], v[242:243]
	v_pk_fma_f32 v[164:165], v[68:69], v[108:109], v[240:241]
	v_pk_fma_f32 v[190:191], v[72:73], v[112:113], v[236:237]
	v_add_co_u32_e32 v236, vcc, 0x48000, v148
	s_nop 1
	v_addc_co_u32_e32 v237, vcc, 0, v149, vcc
	v_lshl_add_u64 v[236:237], v[236:237], 2, s[24:25]
	global_load_dwordx4 v[240:243], v[236:237], off offset:16
	s_nop 0
	global_load_dwordx4 v[236:239], v[236:237], off
	s_nop 0
	v_cvt_pk_bf16_f32 v162, v190, v191
	v_cvt_pk_bf16_f32 v163, v166, v167
	v_cvt_pk_bf16_f32 v164, v164, v165
	v_cvt_pk_bf16_f32 v165, v192, v193
	flat_store_dwordx4 v[150:151], v[162:165] offset:256
	v_lshl_add_u64 v[150:151], v[148:149], 0, s[18:19]
	v_lshl_add_u64 v[166:167], v[150:151], 2, s[24:25]
	v_lshl_add_u64 v[150:151], v[150:151], 1, s[20:21]
	s_mov_b64 s[18:19], 0x48000
	s_waitcnt vmcnt(7)
	v_pk_fma_f32 v[194:195], v[62:63], v[118:119], v[250:251]
	v_pk_fma_f32 v[164:165], v[60:61], v[116:117], v[248:249]
	v_pk_fma_f32 v[192:193], v[66:67], v[122:123], v[246:247]
	v_pk_fma_f32 v[190:191], v[64:65], v[120:121], v[244:245]
	v_add_co_u32_e32 v244, vcc, 0x48000, v148
	s_nop 1
	v_addc_co_u32_e32 v245, vcc, 0, v149, vcc
	v_lshl_add_u64 v[244:245], v[244:245], 2, s[24:25]
	global_load_dwordx4 v[248:251], v[244:245], off offset:528
	s_nop 0
	global_load_dwordx4 v[244:247], v[244:245], off offset:512
	s_nop 0
	v_cvt_pk_bf16_f32 v162, v190, v191
	v_cvt_pk_bf16_f32 v163, v192, v193
	v_cvt_pk_bf16_f32 v164, v164, v165
	v_cvt_pk_bf16_f32 v165, v194, v195
	flat_store_dwordx4 v[150:151], v[162:165]
	s_waitcnt vmcnt(7)
	v_pk_fma_f32 v[166:167], v[58:59], v[114:115], v[230:231]
	v_pk_fma_f32 v[192:193], v[54:55], v[110:111], v[234:235]
	v_pk_fma_f32 v[164:165], v[52:53], v[108:109], v[232:233]
	v_pk_fma_f32 v[190:191], v[56:57], v[112:113], v[228:229]
	v_add_co_u32_e32 v228, vcc, 0x50000, v148
	s_nop 1
	v_addc_co_u32_e32 v229, vcc, 0, v149, vcc
	v_lshl_add_u64 v[228:229], v[228:229], 2, s[24:25]
	global_load_dwordx4 v[232:235], v[228:229], off offset:16
	s_nop 0
	global_load_dwordx4 v[228:231], v[228:229], off
	s_nop 0
	v_cvt_pk_bf16_f32 v162, v190, v191
	v_cvt_pk_bf16_f32 v163, v166, v167
	v_cvt_pk_bf16_f32 v164, v164, v165
	v_cvt_pk_bf16_f32 v165, v192, v193
	flat_store_dwordx4 v[150:151], v[162:165] offset:256
	v_lshl_add_u64 v[150:151], v[148:149], 0, s[18:19]
	v_lshl_add_u64 v[166:167], v[150:151], 2, s[24:25]
	v_lshl_add_u64 v[150:151], v[150:151], 1, s[20:21]
	s_mov_b64 s[18:19], 0x50000
	s_waitcnt vmcnt(7)
; __device__ __forceinline__ unsigned cvt_pk_bf16(float lo, float hi) { unsigned r; asm volatile("v_cvt_pk_bf16_f32 %0, %1, %2" : "=v"(r) : "v"(lo), "v"(hi)); return r; }
;     __device__ __forceinline__ void operator()(const f32x4 (&acc)[2][2][4][2], const Unit& u, int wr, int wc, int fr, int fq) const {
;     ...
;                 for (int m = 0; m < 4; ++m) { const size_t off = (size_t)(row0 + ai * HALF + m * 16) * 2048 + col0;
; #pragma unroll
;                     for (int bj = 0; bj < 2; ++bj) { const f32x4 x0 = *(const f32x4*)(xin_f + off + bj * HALF), x1 = *(const f32x4*)(xin_f + off + bj * HALF + 4);
;                         const f32x4 v0 = x0 + g0[bj] * acc[ai][bj][m][0], v1 = x1 + g1[bj] * acc[ai][bj][m][1];
;                         u32x4 w; w.x = cvt_pk_bf16(v0[0], v0[1]); w.y = cvt_pk_bf16(v0[2], v0[3]); w.z = cvt_pk_bf16(v1[0], v1[1]); w.w = cvt_pk_bf16(v1[2], v1[3]);
;                         *(u32x4*)(out + off + bj * HALF) = w; } }
	v_pk_fma_f32 v[194:195], v[46:47], v[118:119], v[242:243]
	v_pk_fma_f32 v[164:165], v[44:45], v[116:117], v[240:241]
	v_pk_fma_f32 v[192:193], v[50:51], v[122:123], v[238:239]
	v_pk_fma_f32 v[190:191], v[48:49], v[120:121], v[236:237]
	v_add_co_u32_e32 v236, vcc, 0x50000, v148
	s_nop 1
	v_addc_co_u32_e32 v237, vcc, 0, v149, vcc
	v_lshl_add_u64 v[236:237], v[236:237], 2, s[24:25]
	global_load_dwordx4 v[240:243], v[236:237], off offset:528
	s_nop 0
	global_load_dwordx4 v[236:239], v[236:237], off offset:512
	s_nop 0
	v_cvt_pk_bf16_f32 v162, v190, v191
	v_cvt_pk_bf16_f32 v163, v192, v193
	v_cvt_pk_bf16_f32 v164, v164, v165
	v_cvt_pk_bf16_f32 v165, v194, v195
	flat_store_dwordx4 v[150:151], v[162:165]
	s_waitcnt vmcnt(7)
	v_pk_fma_f32 v[166:167], v[42:43], v[114:115], v[246:247]
	v_pk_fma_f32 v[192:193], v[38:39], v[110:111], v[250:251]
	v_pk_fma_f32 v[164:165], v[36:37], v[108:109], v[248:249]
	v_pk_fma_f32 v[190:191], v[40:41], v[112:113], v[244:245]
	v_add_co_u32_e32 v244, vcc, 0x58000, v148
	s_nop 1
	v_addc_co_u32_e32 v245, vcc, 0, v149, vcc
	v_lshl_add_u64 v[244:245], v[244:245], 2, s[24:25]
	global_load_dwordx4 v[248:251], v[244:245], off offset:16
	s_nop 0
	global_load_dwordx4 v[244:247], v[244:245], off
	s_nop 0
	v_cvt_pk_bf16_f32 v162, v190, v191
	v_cvt_pk_bf16_f32 v163, v166, v167
	v_cvt_pk_bf16_f32 v164, v164, v165
	v_cvt_pk_bf16_f32 v165, v192, v193
	flat_store_dwordx4 v[150:151], v[162:165] offset:256
	v_lshl_add_u64 v[150:151], v[148:149], 0, s[18:19]
	v_lshl_add_u64 v[166:167], v[150:151], 2, s[24:25]
	v_lshl_add_u64 v[150:151], v[150:151], 1, s[20:21]
	s_mov_b64 s[18:19], 0x58000
	s_waitcnt vmcnt(7)
	v_pk_fma_f32 v[194:195], v[30:31], v[118:119], v[234:235]
	v_pk_fma_f32 v[164:165], v[28:29], v[116:117], v[232:233]
	v_pk_fma_f32 v[192:193], v[34:35], v[122:123], v[230:231]
	v_pk_fma_f32 v[190:191], v[32:33], v[120:121], v[228:229]
	v_add_co_u32_e32 v228, vcc, 0x58000, v148
	s_nop 1
	v_addc_co_u32_e32 v229, vcc, 0, v149, vcc
	v_lshl_add_u64 v[228:229], v[228:229], 2, s[24:25]
	global_load_dwordx4 v[232:235], v[228:229], off offset:528
	s_nop 0
	global_load_dwordx4 v[228:231], v[228:229], off offset:512
	s_nop 0
	v_cvt_pk_bf16_f32 v162, v190, v191
	v_cvt_pk_bf16_f32 v163, v192, v193
	v_cvt_pk_bf16_f32 v164, v164, v165
	v_cvt_pk_bf16_f32 v165, v194, v195
	flat_store_dwordx4 v[150:151], v[162:165]
	s_waitcnt vmcnt(7)
	v_pk_fma_f32 v[166:167], v[26:27], v[114:115], v[238:239]
	v_pk_fma_f32 v[190:191], v[24:25], v[112:113], v[236:237]
	v_pk_fma_f32 v[192:193], v[22:23], v[110:111], v[242:243]
	v_pk_fma_f32 v[164:165], v[20:21], v[108:109], v[240:241]
	v_cvt_pk_bf16_f32 v162, v190, v191
	v_cvt_pk_bf16_f32 v163, v166, v167
	v_lshl_add_u64 v[166:167], v[148:149], 0, s[18:19]
	v_cvt_pk_bf16_f32 v164, v164, v165
	v_cvt_pk_bf16_f32 v165, v192, v193
	flat_store_dwordx4 v[150:151], v[162:165] offset:256
	v_lshl_add_u64 v[190:191], v[166:167], 2, s[24:25]
	s_waitcnt vmcnt(5)
	v_pk_fma_f32 v[192:193], v[14:15], v[118:119], v[250:251]
	v_pk_fma_f32 v[162:163], v[16:17], v[120:121], v[244:245]
	v_pk_fma_f32 v[150:151], v[12:13], v[116:117], v[248:249]
	v_cvt_pk_bf16_f32 v148, v162, v163
	v_lshl_add_u64 v[162:163], v[166:167], 1, s[20:21]
	v_pk_fma_f32 v[164:165], v[18:19], v[122:123], v[246:247]
	s_nop 0
	v_cvt_pk_bf16_f32 v149, v164, v165
	v_cvt_pk_bf16_f32 v150, v150, v151
	v_cvt_pk_bf16_f32 v151, v192, v193
	flat_store_dwordx4 v[162:163], v[148:151]
	s_waitcnt vmcnt(3)
	v_pk_fma_f32 v[190:191], v[6:7], v[110:111], v[234:235]
	v_pk_fma_f32 v[150:151], v[4:5], v[108:109], v[232:233]
	v_pk_fma_f32 v[166:167], v[10:11], v[114:115], v[230:231]
	v_pk_fma_f32 v[164:165], v[8:9], v[112:113], v[228:229]
	s_nop 0
	v_cvt_pk_bf16_f32 v148, v164, v165
	v_cvt_pk_bf16_f32 v149, v166, v167
	v_cvt_pk_bf16_f32 v150, v150, v151
	v_cvt_pk_bf16_f32 v151, v190, v191
	s_cbranch_execnz .LBB0_667
